# P7 K-loop: all 16 LDS-DMA loads use saddr form (32-bit VGPR offset + SGPR base kept by SALU), removing 16 64-bit VALU address adds per iteration
# speedup vs baseline: 1.0061x; 1.0061x over previous
; #define PG8_STAGE(bufoff, gbase, voff) do { _Pragma("unroll") for (int _i = 0; _i < 2; ++_i) \
;         __builtin_amdgcn_global_load_lds((const unsigned*)((const char*)(gbase) + (voff)[_i]), (LAS unsigned*)(lds + (bufoff) + ldsw + _i * 8192), 16, 0, 0); } while (0)
; #define PG8_LDA(dst, b, h) do { _Pragma("unroll") for (int m = 0; m < 4; ++m) _Pragma("unroll") for (int k = 0; k < 2; ++k) dst[m][k] = *(const LAS bf16x8*)(lds + PG8_SA(b, h) + aoff + m * 2048 + k * 1024); } while (0)
; #define PG8_LDB(dst, b, h) do { _Pragma("unroll") for (int n = 0; n < 2; ++n) _Pragma("unroll") for (int k = 0; k < 2; ++k) dst[n][k] = *(const LAS bf16x8*)(lds + PG8_SB(b, h) + boff + n * 2048 + k * 1024); } while (0)
; #define PG8_MMA(ai, bj, At, Bt) do { __builtin_amdgcn_s_setprio(1); _Pragma("unroll") for (int m = 0; m < 4; ++m) _Pragma("unroll") for (int n = 0; n < 2; ++n) _Pragma("unroll") for (int k = 0; k < 2; ++k) \
;         acc[ai][bj][m][n] = __builtin_amdgcn_mfma_f32_16x16x32_bf16(Bt[n][k], At[m][k], acc[ai][bj][m][n], 0, 0, 0); __builtin_amdgcn_s_setprio(0); } while (0)
; #define PG8_WAIT_V(n) asm volatile("s_waitcnt vmcnt(" #n ")" ::: "memory")
; #define PG8_WAIT_L(n) asm volatile("s_waitcnt lgkmcnt(" #n ")" ::: "memory")
; #define PG8_BAR __builtin_amdgcn_s_barrier()
; #define PG8_SCHED __builtin_amdgcn_sched_barrier(0)
; template <class Epi, class Sched>
; __device__ __forceinline__ void gemm_phase(LAS unsigned char* lds, const Gemm g, const Sched& S, const Epi& E) {
;     ...
;         for (int t = 0; t < nt; t += 2) {
;             const bool last = (t == nt - 2);
;             const char* a1 = cA + (size_t)(t + 1) * kstep;
;             const char* a2 = last ? nA : cA + (size_t)(t + 2) * kstep; const char* b2 = last ? nB : cB + (size_t)(t + 2) * kstep;
;             const char* a3 = a2 + kstep; const char* b3 = b2 + kstep;
;             PG8_LDB(B0, 0, 0); PG8_LDB(B1, 0, 1); PG8_SCHED; PG8_LDA(At, 0, 0); PG8_STAGE(PG8_SA(1, 1), a1 + hstepA, voffA);
;             PG8_WAIT_V(8); PG8_WAIT_L(0); PG8_BAR; PG8_MMA(0, 0, At, B0); PG8_MMA(0, 1, At, B1); PG8_BAR; PG8_SCHED;
;             PG8_LDA(At, 0, 1); PG8_STAGE(PG8_SB(0, 0), b2, voffB); PG8_STAGE(PG8_SB(0, 1), b2 + hstepB, voffB); PG8_STAGE(PG8_SA(0, 0), a2, voffA);
;             PG8_WAIT_V(8); PG8_WAIT_L(0); PG8_BAR; PG8_MMA(1, 0, At, B0); PG8_MMA(1, 1, At, B1); PG8_BAR; PG8_SCHED;
.Ledge_p7:
.LBB0_837:
	ds_read_b128 v[146:149], v155
	ds_read_b128 v[160:163], v155 offset:1024
	ds_read_b128 v[164:167], v155 offset:2048
	ds_read_b128 v[168:171], v155 offset:3072
	ds_read_b128 v[172:175], v156
	ds_read_b128 v[176:179], v156 offset:1024
	ds_read_b128 v[180:183], v156 offset:2048
	ds_read_b128 v[184:187], v156 offset:3072
	s_add_u32 s38, s36, 0xfff80800
	s_addc_u32 s39, s37, -1
	s_cmp_eq_u32 s55, 28
	s_cselect_b32 s41, s19, s39
	s_cselect_b32 s40, s51, s38
	s_cselect_b32 s39, s17, s54
	s_cselect_b32 s38, s52, s53
	s_add_i32 m0, s25, 0xc000
	ds_read_b128 v[188:191], v157
	ds_read_b128 v[192:195], v157 offset:1024
	ds_read_b128 v[196:199], v157 offset:2048
	ds_read_b128 v[200:203], v157 offset:3072
	ds_read_b128 v[204:207], v157 offset:4096
	ds_read_b128 v[208:211], v157 offset:5120
	ds_read_b128 v[212:215], v157 offset:6144
	ds_read_b128 v[216:219], v157 offset:7168
	global_load_lds_dwordx4 v138, s[36:37]
	s_add_i32 m0, s25, 0xe000
	s_nop 0
	global_load_lds_dwordx4 v140, s[36:37]
	s_waitcnt vmcnt(8)
	s_waitcnt lgkmcnt(0)
	s_barrier
	s_setprio 1
	s_waitcnt lgkmcnt(0)
	v_mfma_f32_16x16x32_bf16 v[124:127], v[146:149], v[188:191], v[124:127]
	v_mfma_f32_16x16x32_bf16 v[120:123], v[164:167], v[188:191], v[120:123]
	v_mfma_f32_16x16x32_bf16 v[108:111], v[146:149], v[196:199], v[108:111]
	v_mfma_f32_16x16x32_bf16 v[104:107], v[164:167], v[196:199], v[104:107]
	v_mfma_f32_16x16x32_bf16 v[92:95], v[146:149], v[204:207], v[92:95]
	v_mfma_f32_16x16x32_bf16 v[88:91], v[164:167], v[204:207], v[88:91]
	v_mfma_f32_16x16x32_bf16 v[76:79], v[146:149], v[212:215], v[76:79]
	v_mfma_f32_16x16x32_bf16 v[72:75], v[164:167], v[212:215], v[72:75]
	v_mfma_f32_16x16x32_bf16 v[124:127], v[160:163], v[192:195], v[124:127]
	v_mfma_f32_16x16x32_bf16 v[120:123], v[168:171], v[192:195], v[120:123]
	v_mfma_f32_16x16x32_bf16 v[108:111], v[160:163], v[200:203], v[108:111]
	v_mfma_f32_16x16x32_bf16 v[104:107], v[168:171], v[200:203], v[104:107]
	v_mfma_f32_16x16x32_bf16 v[92:95], v[160:163], v[208:211], v[92:95]
	v_mfma_f32_16x16x32_bf16 v[88:91], v[168:171], v[208:211], v[88:91]
	v_mfma_f32_16x16x32_bf16 v[76:79], v[160:163], v[216:219], v[76:79]
	v_mfma_f32_16x16x32_bf16 v[72:75], v[168:171], v[216:219], v[72:75]
	s_setprio 0
	s_setprio 1
	v_mfma_f32_16x16x32_bf16 v[116:119], v[172:175], v[188:191], v[116:119]
	v_mfma_f32_16x16x32_bf16 v[112:115], v[180:183], v[188:191], v[112:115]
	v_mfma_f32_16x16x32_bf16 v[100:103], v[172:175], v[196:199], v[100:103]
	v_mfma_f32_16x16x32_bf16 v[96:99], v[180:183], v[196:199], v[96:99]
	v_mfma_f32_16x16x32_bf16 v[84:87], v[172:175], v[204:207], v[84:87]
	v_mfma_f32_16x16x32_bf16 v[80:83], v[180:183], v[204:207], v[80:83]
	v_mfma_f32_16x16x32_bf16 v[68:71], v[172:175], v[212:215], v[68:71]
	v_mfma_f32_16x16x32_bf16 v[64:67], v[180:183], v[212:215], v[64:67]
	v_mfma_f32_16x16x32_bf16 v[116:119], v[176:179], v[192:195], v[116:119]
	v_mfma_f32_16x16x32_bf16 v[112:115], v[184:187], v[192:195], v[112:115]
	v_mfma_f32_16x16x32_bf16 v[100:103], v[176:179], v[200:203], v[100:103]
	v_mfma_f32_16x16x32_bf16 v[96:99], v[184:187], v[200:203], v[96:99]
	v_mfma_f32_16x16x32_bf16 v[84:87], v[176:179], v[208:211], v[84:87]
	v_mfma_f32_16x16x32_bf16 v[80:83], v[184:187], v[208:211], v[80:83]
	v_mfma_f32_16x16x32_bf16 v[68:71], v[176:179], v[216:219], v[68:71]
	v_mfma_f32_16x16x32_bf16 v[64:67], v[184:187], v[216:219], v[64:67]
	s_setprio 0
	s_barrier
	s_add_i32 s48, s46, s5
	s_mov_b32 m0, s48
	ds_read_b128 v[188:191], v157 offset:16384
	ds_read_b128 v[192:195], v157 offset:17408
	ds_read_b128 v[196:199], v157 offset:18432
	ds_read_b128 v[200:203], v157 offset:19456
	ds_read_b128 v[204:207], v157 offset:20480
	ds_read_b128 v[208:211], v157 offset:21504
	ds_read_b128 v[212:215], v157 offset:22528
	ds_read_b128 v[216:219], v157 offset:23552
	global_load_lds_dwordx4 v130, s[38:39]
	s_add_i32 m0, s48, 0x2000
	s_add_u32 s48, s38, 0x80000
	s_addc_u32 s49, s39, 0
	s_add_i32 s56, s47, s5
	global_load_lds_dwordx4 v134, s[38:39]
	s_mov_b32 m0, s56
	s_nop 0
	global_load_lds_dwordx4 v130, s[48:49]
	s_add_i32 m0, s56, 0x2000
	s_nop 0
	global_load_lds_dwordx4 v134, s[48:49]
	s_mov_b32 m0, s25
	s_nop 0
	global_load_lds_dwordx4 v128, s[40:41]
	s_mov_b32 m0, s33
	s_nop 0
	global_load_lds_dwordx4 v132, s[40:41]
	s_waitcnt vmcnt(8)
	s_waitcnt lgkmcnt(0)
	s_barrier
	s_setprio 1
	s_waitcnt lgkmcnt(0)
	v_mfma_f32_16x16x32_bf16 v[60:63], v[146:149], v[188:191], v[60:63]
	v_mfma_f32_16x16x32_bf16 v[56:59], v[164:167], v[188:191], v[56:59]
	v_mfma_f32_16x16x32_bf16 v[44:47], v[146:149], v[196:199], v[44:47]
	v_mfma_f32_16x16x32_bf16 v[40:43], v[164:167], v[196:199], v[40:43]
	v_mfma_f32_16x16x32_bf16 v[28:31], v[146:149], v[204:207], v[28:31]
	v_mfma_f32_16x16x32_bf16 v[24:27], v[164:167], v[204:207], v[24:27]
	v_mfma_f32_16x16x32_bf16 v[12:15], v[146:149], v[212:215], v[12:15]
	v_mfma_f32_16x16x32_bf16 v[8:11], v[164:167], v[212:215], v[8:11]
	v_mfma_f32_16x16x32_bf16 v[60:63], v[160:163], v[192:195], v[60:63]
	v_mfma_f32_16x16x32_bf16 v[56:59], v[168:171], v[192:195], v[56:59]
	v_mfma_f32_16x16x32_bf16 v[44:47], v[160:163], v[200:203], v[44:47]
	v_mfma_f32_16x16x32_bf16 v[40:43], v[168:171], v[200:203], v[40:43]
	v_mfma_f32_16x16x32_bf16 v[28:31], v[160:163], v[208:211], v[28:31]
	v_mfma_f32_16x16x32_bf16 v[24:27], v[168:171], v[208:211], v[24:27]
	v_mfma_f32_16x16x32_bf16 v[12:15], v[160:163], v[216:219], v[12:15]
	v_mfma_f32_16x16x32_bf16 v[8:11], v[168:171], v[216:219], v[8:11]
	s_setprio 0
	s_setprio 1
	v_mfma_f32_16x16x32_bf16 v[52:55], v[172:175], v[188:191], v[52:55]
	v_mfma_f32_16x16x32_bf16 v[48:51], v[180:183], v[188:191], v[48:51]
	v_mfma_f32_16x16x32_bf16 v[36:39], v[172:175], v[196:199], v[36:39]
	v_mfma_f32_16x16x32_bf16 v[32:35], v[180:183], v[196:199], v[32:35]
	v_mfma_f32_16x16x32_bf16 v[20:23], v[172:175], v[204:207], v[20:23]
	v_mfma_f32_16x16x32_bf16 v[16:19], v[180:183], v[204:207], v[16:19]
	v_mfma_f32_16x16x32_bf16 v[4:7], v[172:175], v[212:215], v[4:7]
	v_mfma_f32_16x16x32_bf16 v[0:3], v[180:183], v[212:215], v[0:3]
	v_mfma_f32_16x16x32_bf16 v[52:55], v[176:179], v[192:195], v[52:55]
	v_mfma_f32_16x16x32_bf16 v[48:51], v[184:187], v[192:195], v[48:51]
	v_mfma_f32_16x16x32_bf16 v[36:39], v[176:179], v[200:203], v[36:39]
	v_mfma_f32_16x16x32_bf16 v[32:35], v[184:187], v[200:203], v[32:35]
	v_mfma_f32_16x16x32_bf16 v[20:23], v[176:179], v[208:211], v[20:23]
	v_mfma_f32_16x16x32_bf16 v[16:19], v[184:187], v[208:211], v[16:19]
	v_mfma_f32_16x16x32_bf16 v[4:7], v[176:179], v[216:219], v[4:7]
	v_mfma_f32_16x16x32_bf16 v[0:3], v[184:187], v[216:219], v[0:3]
	s_setprio 0
	s_barrier
; #define PG8_STAGE(bufoff, gbase, voff) do { _Pragma("unroll") for (int _i = 0; _i < 2; ++_i) \
;         __builtin_amdgcn_global_load_lds((const unsigned*)((const char*)(gbase) + (voff)[_i]), (LAS unsigned*)(lds + (bufoff) + ldsw + _i * 8192), 16, 0, 0); } while (0)
; #define PG8_LDA(dst, b, h) do { _Pragma("unroll") for (int m = 0; m < 4; ++m) _Pragma("unroll") for (int k = 0; k < 2; ++k) dst[m][k] = *(const LAS bf16x8*)(lds + PG8_SA(b, h) + aoff + m * 2048 + k * 1024); } while (0)
; #define PG8_LDB(dst, b, h) do { _Pragma("unroll") for (int n = 0; n < 2; ++n) _Pragma("unroll") for (int k = 0; k < 2; ++k) dst[n][k] = *(const LAS bf16x8*)(lds + PG8_SB(b, h) + boff + n * 2048 + k * 1024); } while (0)
; #define PG8_MMA(ai, bj, At, Bt) do { __builtin_amdgcn_s_setprio(1); _Pragma("unroll") for (int m = 0; m < 4; ++m) _Pragma("unroll") for (int n = 0; n < 2; ++n) _Pragma("unroll") for (int k = 0; k < 2; ++k) \
;         acc[ai][bj][m][n] = __builtin_amdgcn_mfma_f32_16x16x32_bf16(Bt[n][k], At[m][k], acc[ai][bj][m][n], 0, 0, 0); __builtin_amdgcn_s_setprio(0); } while (0)
; #define PG8_WAIT_V(n) asm volatile("s_waitcnt vmcnt(" #n ")" ::: "memory")
; #define PG8_WAIT_L(n) asm volatile("s_waitcnt lgkmcnt(" #n ")" ::: "memory")
; #define PG8_BAR __builtin_amdgcn_s_barrier()
; #define PG8_SCHED __builtin_amdgcn_sched_barrier(0)
; template <class Epi, class Sched>
; __device__ __forceinline__ void gemm_phase(LAS unsigned char* lds, const Gemm g, const Sched& S, const Epi& E) {
;     ...
;             PG8_LDB(B0, 1, 0); PG8_LDB(B1, 1, 1); PG8_SCHED; PG8_LDA(At, 1, 0); PG8_STAGE(PG8_SA(0, 1), a2 + hstepA, voffA);
;             PG8_WAIT_V(8); PG8_WAIT_L(0); PG8_BAR; PG8_MMA(0, 0, At, B0); PG8_MMA(0, 1, At, B1); PG8_BAR; PG8_SCHED;
;             PG8_LDA(At, 1, 1); PG8_STAGE(PG8_SB(1, 0), b3, voffB); PG8_STAGE(PG8_SB(1, 1), b3 + hstepB, voffB); PG8_STAGE(PG8_SA(1, 0), a3, voffA);
;             PG8_WAIT_V(8); PG8_WAIT_L(0); PG8_BAR; PG8_MMA(1, 0, At, B0); PG8_MMA(1, 1, At, B1); PG8_BAR; PG8_SCHED;
;         }
	s_add_i32 s48, 0, 0x18000
	v_add_u32_e32 v159, s48, v153
	s_add_i32 s49, 0, 0x1c000
	ds_read_b128 v[146:149], v159
	ds_read_b128 v[160:163], v159 offset:1024
	ds_read_b128 v[164:167], v159 offset:2048
	ds_read_b128 v[168:171], v159 offset:3072
	v_add_u32_e32 v159, s49, v153
	ds_read_b128 v[172:175], v159
	ds_read_b128 v[176:179], v159 offset:1024
	ds_read_b128 v[180:183], v159 offset:2048
	ds_read_b128 v[184:187], v159 offset:3072
	s_add_u32 s40, s40, 0x80000
	s_addc_u32 s41, s41, 0
	s_mov_b32 m0, s34
	ds_read_b128 v[188:191], v157 offset:32768
	ds_read_b128 v[192:195], v157 offset:33792
	ds_read_b128 v[196:199], v157 offset:34816
	ds_read_b128 v[200:203], v157 offset:35840
	ds_read_b128 v[204:207], v157 offset:36864
	ds_read_b128 v[208:211], v157 offset:37888
	ds_read_b128 v[212:215], v157 offset:38912
	ds_read_b128 v[216:219], v157 offset:39936
	global_load_lds_dwordx4 v128, s[40:41]
	s_mov_b32 m0, s35
	s_nop 0
	global_load_lds_dwordx4 v132, s[40:41]
	s_waitcnt vmcnt(8)
	s_waitcnt lgkmcnt(0)
	s_barrier
	s_setprio 1
	s_waitcnt lgkmcnt(0)
	v_mfma_f32_16x16x32_bf16 v[124:127], v[146:149], v[188:191], v[124:127]
	v_mfma_f32_16x16x32_bf16 v[120:123], v[164:167], v[188:191], v[120:123]
	v_mfma_f32_16x16x32_bf16 v[108:111], v[146:149], v[196:199], v[108:111]
	v_mfma_f32_16x16x32_bf16 v[104:107], v[164:167], v[196:199], v[104:107]
	v_mfma_f32_16x16x32_bf16 v[92:95], v[146:149], v[204:207], v[92:95]
	v_mfma_f32_16x16x32_bf16 v[88:91], v[164:167], v[204:207], v[88:91]
	v_mfma_f32_16x16x32_bf16 v[76:79], v[146:149], v[212:215], v[76:79]
	v_mfma_f32_16x16x32_bf16 v[72:75], v[164:167], v[212:215], v[72:75]
	v_mfma_f32_16x16x32_bf16 v[124:127], v[160:163], v[192:195], v[124:127]
	v_mfma_f32_16x16x32_bf16 v[120:123], v[168:171], v[192:195], v[120:123]
	v_mfma_f32_16x16x32_bf16 v[108:111], v[160:163], v[200:203], v[108:111]
	v_mfma_f32_16x16x32_bf16 v[104:107], v[168:171], v[200:203], v[104:107]
	v_mfma_f32_16x16x32_bf16 v[92:95], v[160:163], v[208:211], v[92:95]
	v_mfma_f32_16x16x32_bf16 v[88:91], v[168:171], v[208:211], v[88:91]
	v_mfma_f32_16x16x32_bf16 v[76:79], v[160:163], v[216:219], v[76:79]
	v_mfma_f32_16x16x32_bf16 v[72:75], v[168:171], v[216:219], v[72:75]
	s_setprio 0
	s_setprio 1
	v_mfma_f32_16x16x32_bf16 v[116:119], v[172:175], v[188:191], v[116:119]
	v_mfma_f32_16x16x32_bf16 v[112:115], v[180:183], v[188:191], v[112:115]
	v_mfma_f32_16x16x32_bf16 v[100:103], v[172:175], v[196:199], v[100:103]
	v_mfma_f32_16x16x32_bf16 v[96:99], v[180:183], v[196:199], v[96:99]
	v_mfma_f32_16x16x32_bf16 v[84:87], v[172:175], v[204:207], v[84:87]
	v_mfma_f32_16x16x32_bf16 v[80:83], v[180:183], v[204:207], v[80:83]
	v_mfma_f32_16x16x32_bf16 v[68:71], v[172:175], v[212:215], v[68:71]
	v_mfma_f32_16x16x32_bf16 v[64:67], v[180:183], v[212:215], v[64:67]
	v_mfma_f32_16x16x32_bf16 v[116:119], v[176:179], v[192:195], v[116:119]
	v_mfma_f32_16x16x32_bf16 v[112:115], v[184:187], v[192:195], v[112:115]
	v_mfma_f32_16x16x32_bf16 v[100:103], v[176:179], v[200:203], v[100:103]
	v_mfma_f32_16x16x32_bf16 v[96:99], v[184:187], v[200:203], v[96:99]
	v_mfma_f32_16x16x32_bf16 v[84:87], v[176:179], v[208:211], v[84:87]
	v_mfma_f32_16x16x32_bf16 v[80:83], v[184:187], v[208:211], v[80:83]
	v_mfma_f32_16x16x32_bf16 v[68:71], v[176:179], v[216:219], v[68:71]
	v_mfma_f32_16x16x32_bf16 v[64:67], v[184:187], v[216:219], v[64:67]
	s_setprio 0
	s_barrier
	s_add_i32 s56, s48, s5
	s_add_u32 s100, s38, 0x80
	s_addc_u32 s101, s39, 0
	s_mov_b32 m0, s56
	ds_read_b128 v[188:191], v157 offset:49152
	ds_read_b128 v[192:195], v157 offset:50176
	ds_read_b128 v[196:199], v157 offset:51200
	ds_read_b128 v[200:203], v157 offset:52224
	ds_read_b128 v[204:207], v157 offset:53248
	ds_read_b128 v[208:211], v157 offset:54272
	ds_read_b128 v[212:215], v157 offset:55296
	ds_read_b128 v[216:219], v157 offset:56320
	global_load_lds_dwordx4 v130, s[100:101]
	s_add_i32 m0, s56, 0x2000
	s_add_u32 s38, s38, 0x80080
	s_addc_u32 s39, s39, 0
	s_add_i32 s56, s49, s5
	global_load_lds_dwordx4 v134, s[100:101]
	s_mov_b32 m0, s56
	s_nop 0
	global_load_lds_dwordx4 v130, s[38:39]
	s_add_i32 m0, s56, 0x2000
	s_nop 0
	global_load_lds_dwordx4 v134, s[38:39]
	s_add_u32 s100, s40, 0xfff80800
	s_addc_u32 s101, s41, -1
	s_mov_b32 m0, s43
	s_nop 0
	global_load_lds_dwordx4 v128, s[100:101]
	s_mov_b32 m0, s44
	s_nop 0
	global_load_lds_dwordx4 v132, s[100:101]
	s_waitcnt vmcnt(8)
	s_waitcnt lgkmcnt(0)
	s_barrier
	s_setprio 1
	s_waitcnt lgkmcnt(0)
	v_mfma_f32_16x16x32_bf16 v[60:63], v[146:149], v[188:191], v[60:63]
	v_mfma_f32_16x16x32_bf16 v[56:59], v[164:167], v[188:191], v[56:59]
	v_mfma_f32_16x16x32_bf16 v[44:47], v[146:149], v[196:199], v[44:47]
	v_mfma_f32_16x16x32_bf16 v[40:43], v[164:167], v[196:199], v[40:43]
	v_mfma_f32_16x16x32_bf16 v[28:31], v[146:149], v[204:207], v[28:31]
	v_mfma_f32_16x16x32_bf16 v[24:27], v[164:167], v[204:207], v[24:27]
	v_mfma_f32_16x16x32_bf16 v[12:15], v[146:149], v[212:215], v[12:15]
	v_mfma_f32_16x16x32_bf16 v[8:11], v[164:167], v[212:215], v[8:11]
	v_mfma_f32_16x16x32_bf16 v[60:63], v[160:163], v[192:195], v[60:63]
	v_mfma_f32_16x16x32_bf16 v[56:59], v[168:171], v[192:195], v[56:59]
	v_mfma_f32_16x16x32_bf16 v[44:47], v[160:163], v[200:203], v[44:47]
	v_mfma_f32_16x16x32_bf16 v[40:43], v[168:171], v[200:203], v[40:43]
	v_mfma_f32_16x16x32_bf16 v[28:31], v[160:163], v[208:211], v[28:31]
	v_mfma_f32_16x16x32_bf16 v[24:27], v[168:171], v[208:211], v[24:27]
	v_mfma_f32_16x16x32_bf16 v[12:15], v[160:163], v[216:219], v[12:15]
	v_mfma_f32_16x16x32_bf16 v[8:11], v[168:171], v[216:219], v[8:11]
	s_setprio 0
	s_setprio 1
	v_mfma_f32_16x16x32_bf16 v[52:55], v[172:175], v[188:191], v[52:55]
	v_mfma_f32_16x16x32_bf16 v[48:51], v[180:183], v[188:191], v[48:51]
	v_mfma_f32_16x16x32_bf16 v[36:39], v[172:175], v[196:199], v[36:39]
	v_mfma_f32_16x16x32_bf16 v[32:35], v[180:183], v[196:199], v[32:35]
	v_mfma_f32_16x16x32_bf16 v[20:23], v[172:175], v[204:207], v[20:23]
	v_mfma_f32_16x16x32_bf16 v[16:19], v[180:183], v[204:207], v[16:19]
	v_mfma_f32_16x16x32_bf16 v[4:7], v[172:175], v[212:215], v[4:7]
	v_mfma_f32_16x16x32_bf16 v[0:3], v[180:183], v[212:215], v[0:3]
	v_mfma_f32_16x16x32_bf16 v[52:55], v[176:179], v[192:195], v[52:55]
	v_mfma_f32_16x16x32_bf16 v[48:51], v[184:187], v[192:195], v[48:51]
	v_mfma_f32_16x16x32_bf16 v[36:39], v[176:179], v[200:203], v[36:39]
	v_mfma_f32_16x16x32_bf16 v[32:35], v[184:187], v[200:203], v[32:35]
	v_mfma_f32_16x16x32_bf16 v[20:23], v[176:179], v[208:211], v[20:23]
	v_mfma_f32_16x16x32_bf16 v[16:19], v[184:187], v[208:211], v[16:19]
	v_mfma_f32_16x16x32_bf16 v[4:7], v[176:179], v[216:219], v[4:7]
	v_mfma_f32_16x16x32_bf16 v[0:3], v[184:187], v[216:219], v[0:3]
	s_setprio 0
	s_barrier
	s_add_i32 s55, s55, 2
	s_add_u32 s36, s36, 0x1000
	s_addc_u32 s37, s37, 0
	s_add_u32 s53, s53, 0x100
	s_addc_u32 s54, s54, 0
	s_cmp_gt_u32 s55, 29
	s_cbranch_scc0 .LBB0_837
	s_and_b64 vcc, exec, s[12:13]
	s_cbranch_vccz .LBB0_840
	s_barrier
